# re-measure v6 (G2 write-through) to check drift
# baseline (speedup 1.0000x reference)
.Lg2_vec_issued:
	buffer_load_dwordx4 v[2:5], v140, s[24:27], 0 offen
	buffer_load_dwordx4 v[6:9], v140, s[44:47], 0 offen
	buffer_load_dwordx4 v[10:13], v140, s[24:27], s33 offen
	buffer_load_dwordx4 v[14:17], v140, s[44:47], s33 offen
	buffer_load_dwordx4 v[18:21], v140, s[24:27], s29 offen
	buffer_load_dwordx4 v[22:25], v140, s[44:47], s29 offen
	buffer_load_dwordx4 v[26:29], v140, s[24:27], s3 offen
	buffer_load_dwordx4 v[30:33], v140, s[44:47], s3 offen
	s_movk_i32 s1, 0x90
	v_mul_lo_u32 v34, v34, s1
	s_add_u32 s56, s44, 0x80
	v_lshl_add_u32 v139, v35, 1, v34
	s_addc_u32 s0, vcc_lo, 0
	s_and_b32 s57, s0, 0xffff
	s_movk_i32 s0, 0x80
	s_mov_b32 s58, s26
	s_mov_b32 s59, s27
	v_and_b32_e32 v137, 31, v136
	v_bfe_u32 v138, v136, 5, 1
	s_mov_b32 s42, s26
	s_mov_b32 s43, s27
	s_mov_b32 vcc_hi, 0
	v_add_u32_e32 v142, 0xd800, v139
	s_waitcnt vmcnt(7)
	ds_write_b128 v139, v[2:5]
	s_waitcnt vmcnt(6)
	ds_write_b128 v139, v[6:9] offset:36864
	s_waitcnt vmcnt(5)
	ds_write_b128 v139, v[10:13] offset:4608
	s_waitcnt vmcnt(4)
	ds_write_b128 v139, v[14:17] offset:41472
	s_waitcnt vmcnt(3)
	ds_write_b128 v139, v[18:21] offset:9216
	s_waitcnt vmcnt(2)
	ds_write_b128 v139, v[22:25] offset:46080
	s_waitcnt vmcnt(1)
	ds_write_b128 v139, v[26:29] offset:13824
	s_waitcnt vmcnt(0)
	ds_write_b128 v139, v[30:33] offset:50688
	buffer_load_dwordx4 v[94:97], v140, s[24:27], s0 offen
	buffer_load_dwordx4 v[252:255], v140, s[24:27], s0 offen
	buffer_load_dwordx4 v[90:93], v140, s[56:59], 0 offen
	buffer_load_dwordx4 v[252:255], v140, s[56:59], 0 offen
	s_mov_b32 s0, 0x11080
	buffer_load_dwordx4 v[86:89], v140, s[24:27], s0 offen
	buffer_load_dwordx4 v[252:255], v140, s[24:27], s0 offen
	buffer_load_dwordx4 v[82:85], v140, s[56:59], s33 offen
	buffer_load_dwordx4 v[252:255], v140, s[56:59], s33 offen
	s_mov_b32 s0, 0x22080
	buffer_load_dwordx4 v[78:81], v140, s[24:27], s0 offen
	buffer_load_dwordx4 v[252:255], v140, s[24:27], s0 offen
	buffer_load_dwordx4 v[74:77], v140, s[56:59], s29 offen
	buffer_load_dwordx4 v[252:255], v140, s[56:59], s29 offen
	s_mov_b32 s0, 0x33080
	buffer_load_dwordx4 v[70:73], v140, s[24:27], s0 offen
	buffer_load_dwordx4 v[252:255], v140, s[24:27], s0 offen
	buffer_load_dwordx4 v[66:69], v140, s[56:59], s3 offen
	buffer_load_dwordx4 v[252:255], v140, s[56:59], s3 offen
	s_add_u32 s56, s44, 0x100
	s_addc_u32 s0, vcc_lo, 0
	s_and_b32 s57, s0, 0xffff
	s_mov_b32 s0, 0x11100
	buffer_load_dwordx4 v[102:105], v140, s[24:27], s50 offen
	buffer_load_dwordx4 v[252:255], v140, s[24:27], s50 offen
	buffer_load_dwordx4 v[98:101], v140, s[56:59], 0 offen
	buffer_load_dwordx4 v[252:255], v140, s[56:59], 0 offen
	buffer_load_dwordx4 v[106:109], v140, s[24:27], s0 offen
	buffer_load_dwordx4 v[252:255], v140, s[24:27], s0 offen
	buffer_load_dwordx4 v[110:113], v140, s[56:59], s33 offen
	buffer_load_dwordx4 v[252:255], v140, s[56:59], s33 offen
	s_mov_b32 s0, 0x22100
	buffer_load_dwordx4 v[114:117], v140, s[24:27], s0 offen
	buffer_load_dwordx4 v[252:255], v140, s[24:27], s0 offen
	buffer_load_dwordx4 v[118:121], v140, s[56:59], s29 offen
	buffer_load_dwordx4 v[252:255], v140, s[56:59], s29 offen
	s_mov_b32 s0, 0x33100
	buffer_load_dwordx4 v[122:125], v140, s[24:27], s0 offen
	buffer_load_dwordx4 v[252:255], v140, s[24:27], s0 offen
	buffer_load_dwordx4 v[126:129], v140, s[56:59], s3 offen
	buffer_load_dwordx4 v[252:255], v140, s[56:59], s3 offen
	v_ashrrev_i32_e32 v2, 1, v136
	v_and_b32_e32 v141, 0xffffffc0, v2
	v_or_b32_e32 v3, v141, v137
	v_lshlrev_b32_e32 v2, 4, v138
	v_mad_u64_u32 v[130:131], s[0:1], v3, s1, v[2:3]
	v_and_b32_e32 v3, 0x5f, v136
	v_mul_u32_u24_e32 v3, 0x48, v3
	v_lshl_add_u32 v131, v3, 1, v2
	v_mov_b32_e32 v2, 0
	s_mov_b64 s[0:1], 0x180
	v_mov_b32_e32 v3, v2
	v_mov_b32_e32 v4, v2
	v_mov_b32_e32 v5, v2
	v_mov_b32_e32 v6, v2
	v_mov_b32_e32 v7, v2
	v_mov_b32_e32 v8, v2
	v_mov_b32_e32 v9, v2
	v_mov_b32_e32 v10, v2
	v_mov_b32_e32 v11, v2
	v_mov_b32_e32 v12, v2
	v_mov_b32_e32 v13, v2
	v_mov_b32_e32 v14, v2
	v_mov_b32_e32 v15, v2
	v_mov_b32_e32 v16, v2
	v_mov_b32_e32 v17, v2
	v_mov_b32_e32 v18, v2
	v_mov_b32_e32 v19, v2
	v_mov_b32_e32 v20, v2
	v_mov_b32_e32 v21, v2
	v_mov_b32_e32 v22, v2
	v_mov_b32_e32 v23, v2
	v_mov_b32_e32 v24, v2
	v_mov_b32_e32 v25, v2
	v_mov_b32_e32 v26, v2
	v_mov_b32_e32 v27, v2
	v_mov_b32_e32 v28, v2
	v_mov_b32_e32 v29, v2
	v_mov_b32_e32 v30, v2
	v_mov_b32_e32 v31, v2
	v_mov_b32_e32 v32, v2
	v_mov_b32_e32 v33, v2
	v_mov_b32_e32 v34, v2
	v_mov_b32_e32 v35, v2
	v_mov_b32_e32 v36, v2
	v_mov_b32_e32 v37, v2
	v_mov_b32_e32 v38, v2
	v_mov_b32_e32 v39, v2
	v_mov_b32_e32 v40, v2
	v_mov_b32_e32 v41, v2
	v_mov_b32_e32 v42, v2
	v_mov_b32_e32 v43, v2
	v_mov_b32_e32 v44, v2
	v_mov_b32_e32 v45, v2
	v_mov_b32_e32 v46, v2
	v_mov_b32_e32 v47, v2
	v_mov_b32_e32 v48, v2
	v_mov_b32_e32 v49, v2
	v_mov_b32_e32 v50, v2
	v_mov_b32_e32 v51, v2
	v_mov_b32_e32 v52, v2
	v_mov_b32_e32 v53, v2
	v_mov_b32_e32 v54, v2
	v_mov_b32_e32 v55, v2
	v_mov_b32_e32 v56, v2
	v_mov_b32_e32 v57, v2
	v_mov_b32_e32 v58, v2
	v_mov_b32_e32 v59, v2
	v_mov_b32_e32 v60, v2
	v_mov_b32_e32 v61, v2
	v_mov_b32_e32 v62, v2
	v_mov_b32_e32 v63, v2
	v_mov_b32_e32 v64, v2
	v_mov_b32_e32 v65, v2
	s_waitcnt lgkmcnt(0)
	s_barrier
.LBB0_133:
	ds_read_b128 v[178:181], v130
	ds_read_b128 v[182:185], v130 offset:32
	ds_read_b128 v[186:189], v130 offset:4608
	ds_read_b128 v[190:193], v130 offset:4640
	ds_read_b128 v[194:197], v131 offset:36864
	ds_read_b128 v[198:201], v131 offset:36896
	ds_read_b128 v[202:205], v131 offset:41472
	ds_read_b128 v[206:209], v131 offset:41504
	s_waitcnt vmcnt(31)
	ds_write_b128 v139, v[94:97] offset:18432
	buffer_load_dwordx4 v[94:97], v140, s[40:43], s0 offen
	buffer_load_dwordx4 v[252:255], v140, s[40:43], s0 offen
	s_waitcnt lgkmcnt(4)
	v_mfma_f32_32x32x16_bf16 v[50:65], v[178:181], v[194:197], v[50:65]
	s_add_u32 s24, s44, s0
	s_addc_u32 s25, vcc_lo, s1
	s_and_b32 s25, s25, 0xffff
	s_waitcnt lgkmcnt(2)
	v_mfma_f32_32x32x16_bf16 v[34:49], v[178:181], v[202:205], v[34:49]
	s_waitcnt vmcnt(31)
	ds_write_b128 v139, v[90:93] offset:55296
	buffer_load_dwordx4 v[90:93], v140, s[24:27], 0 offen
	buffer_load_dwordx4 v[252:255], v140, s[24:27], 0 offen
	v_mfma_f32_32x32x16_bf16 v[18:33], v[186:189], v[194:197], v[18:33]
	v_mfma_f32_32x32x16_bf16 v[2:17], v[186:189], v[202:205], v[2:17]
	s_add_i32 s34, s0, 0x11000
	ds_read_b128 v[178:181], v130 offset:64
	ds_read_b128 v[186:189], v130 offset:4672
	ds_read_b128 v[194:197], v131 offset:36928
	ds_read_b128 v[202:205], v131 offset:41536
	s_waitcnt vmcnt(31)
	ds_write_b128 v139, v[86:89] offset:23040
	buffer_load_dwordx4 v[86:89], v140, s[40:43], s34 offen
	buffer_load_dwordx4 v[252:255], v140, s[40:43], s34 offen
	v_mfma_f32_32x32x16_bf16 v[50:65], v[182:185], v[198:201], v[50:65]
	s_waitcnt lgkmcnt(7)
	v_mfma_f32_32x32x16_bf16 v[34:49], v[182:185], v[206:209], v[34:49]
	s_waitcnt vmcnt(31)
	ds_write_b128 v139, v[82:85] offset:59904
	buffer_load_dwordx4 v[82:85], v140, s[24:27], s33 offen
	buffer_load_dwordx4 v[252:255], v140, s[24:27], s33 offen
	v_mfma_f32_32x32x16_bf16 v[18:33], v[190:193], v[198:201], v[18:33]
	v_mfma_f32_32x32x16_bf16 v[2:17], v[190:193], v[206:209], v[2:17]
	s_add_i32 s34, s0, 0x22000
	ds_read_b128 v[182:185], v130 offset:96
	ds_read_b128 v[190:193], v130 offset:4704
	ds_read_b128 v[198:201], v131 offset:36960
	ds_read_b128 v[206:209], v131 offset:41568
	s_waitcnt vmcnt(31)
	ds_write_b128 v139, v[78:81] offset:27648
	buffer_load_dwordx4 v[78:81], v140, s[40:43], s34 offen
	buffer_load_dwordx4 v[252:255], v140, s[40:43], s34 offen
	s_waitcnt lgkmcnt(8)
	v_mfma_f32_32x32x16_bf16 v[50:65], v[178:181], v[194:197], v[50:65]
	s_waitcnt lgkmcnt(7)
	v_mfma_f32_32x32x16_bf16 v[34:49], v[178:181], v[202:205], v[34:49]
	s_waitcnt vmcnt(31)
	ds_write_b128 v139, v[74:77] offset:64512
	buffer_load_dwordx4 v[74:77], v140, s[24:27], s29 offen
	buffer_load_dwordx4 v[252:255], v140, s[24:27], s29 offen
	v_mfma_f32_32x32x16_bf16 v[18:33], v[186:189], v[194:197], v[18:33]
	v_mfma_f32_32x32x16_bf16 v[2:17], v[186:189], v[202:205], v[2:17]
	s_add_i32 s34, s0, 0x33000
	s_waitcnt vmcnt(31)
	ds_write_b128 v139, v[70:73] offset:32256
	buffer_load_dwordx4 v[70:73], v140, s[40:43], s34 offen
	buffer_load_dwordx4 v[252:255], v140, s[40:43], s34 offen
	s_waitcnt lgkmcnt(4)
	v_mfma_f32_32x32x16_bf16 v[50:65], v[182:185], v[198:201], v[50:65]
	s_waitcnt lgkmcnt(3)
	v_mfma_f32_32x32x16_bf16 v[34:49], v[182:185], v[206:209], v[34:49]
	s_waitcnt vmcnt(31)
	ds_write_b128 v142, v[66:69] offset:13824
	buffer_load_dwordx4 v[66:69], v140, s[24:27], s3 offen
	buffer_load_dwordx4 v[252:255], v140, s[24:27], s3 offen
	v_mfma_f32_32x32x16_bf16 v[18:33], v[190:193], v[198:201], v[18:33]
	v_mfma_f32_32x32x16_bf16 v[2:17], v[190:193], v[206:209], v[2:17]
	s_min_u32 s24, vcc_hi, 11
	s_lshl_b32 s34, s24, 7
	s_add_i32 s24, s34, 0x200
	s_waitcnt lgkmcnt(0)
	s_barrier
	ds_read_b128 v[178:181], v130 offset:18432
	ds_read_b128 v[182:185], v130 offset:18464
	ds_read_b128 v[186:189], v130 offset:23040
	ds_read_b128 v[190:193], v130 offset:23072
	ds_read_b128 v[194:197], v131 offset:55296
	ds_read_b128 v[198:201], v131 offset:55328
	ds_read_b128 v[202:205], v131 offset:59904
	ds_read_b128 v[206:209], v131 offset:59936
	s_waitcnt vmcnt(31)
	ds_write_b128 v139, v[102:105]
	buffer_load_dwordx4 v[102:105], v140, s[40:43], s24 offen
	buffer_load_dwordx4 v[252:255], v140, s[40:43], s24 offen
	s_waitcnt lgkmcnt(4)
	v_mfma_f32_32x32x16_bf16 v[50:65], v[178:181], v[194:197], v[50:65]
	s_add_u32 s24, s44, s24
	s_addc_u32 s25, vcc_lo, 0
	s_and_b32 s25, s25, 0xffff
	s_waitcnt lgkmcnt(2)
	v_mfma_f32_32x32x16_bf16 v[34:49], v[178:181], v[202:205], v[34:49]
	s_waitcnt vmcnt(31)
	ds_write_b128 v139, v[98:101] offset:36864
	buffer_load_dwordx4 v[98:101], v140, s[24:27], 0 offen
	buffer_load_dwordx4 v[252:255], v140, s[24:27], 0 offen
	v_mfma_f32_32x32x16_bf16 v[18:33], v[186:189], v[194:197], v[18:33]
	v_mfma_f32_32x32x16_bf16 v[2:17], v[186:189], v[202:205], v[2:17]
	s_add_i32 s35, s34, 0x11200
	ds_read_b128 v[178:181], v130 offset:18496
	ds_read_b128 v[186:189], v130 offset:23104
	ds_read_b128 v[194:197], v131 offset:55360
	ds_read_b128 v[202:205], v131 offset:59968
	s_waitcnt vmcnt(31)
	ds_write_b128 v139, v[106:109] offset:4608
	buffer_load_dwordx4 v[106:109], v140, s[40:43], s35 offen
	buffer_load_dwordx4 v[252:255], v140, s[40:43], s35 offen
	v_mfma_f32_32x32x16_bf16 v[50:65], v[182:185], v[198:201], v[50:65]
	s_waitcnt lgkmcnt(7)
	v_mfma_f32_32x32x16_bf16 v[34:49], v[182:185], v[206:209], v[34:49]
	s_waitcnt vmcnt(31)
	ds_write_b128 v139, v[110:113] offset:41472
	buffer_load_dwordx4 v[110:113], v140, s[24:27], s33 offen
	buffer_load_dwordx4 v[252:255], v140, s[24:27], s33 offen
	v_mfma_f32_32x32x16_bf16 v[18:33], v[190:193], v[198:201], v[18:33]
	v_mfma_f32_32x32x16_bf16 v[2:17], v[190:193], v[206:209], v[2:17]
	s_add_i32 s35, s34, 0x22200
	ds_read_b128 v[182:185], v130 offset:18528
	ds_read_b128 v[190:193], v130 offset:23136
	ds_read_b128 v[198:201], v131 offset:55392
	ds_read_b128 v[206:209], v131 offset:60000
	s_waitcnt vmcnt(31)
	ds_write_b128 v139, v[114:117] offset:9216
	buffer_load_dwordx4 v[114:117], v140, s[40:43], s35 offen
	buffer_load_dwordx4 v[252:255], v140, s[40:43], s35 offen
	s_waitcnt lgkmcnt(8)
	v_mfma_f32_32x32x16_bf16 v[50:65], v[178:181], v[194:197], v[50:65]
	s_waitcnt lgkmcnt(7)
	v_mfma_f32_32x32x16_bf16 v[34:49], v[178:181], v[202:205], v[34:49]
	s_waitcnt vmcnt(31)
	ds_write_b128 v139, v[118:121] offset:46080
	buffer_load_dwordx4 v[118:121], v140, s[24:27], s29 offen
	buffer_load_dwordx4 v[252:255], v140, s[24:27], s29 offen
	v_mfma_f32_32x32x16_bf16 v[18:33], v[186:189], v[194:197], v[18:33]
	v_mfma_f32_32x32x16_bf16 v[2:17], v[186:189], v[202:205], v[2:17]
	s_add_i32 s34, s34, 0x33200
	s_waitcnt vmcnt(31)
	ds_write_b128 v139, v[122:125] offset:13824
	buffer_load_dwordx4 v[122:125], v140, s[40:43], s34 offen
	buffer_load_dwordx4 v[252:255], v140, s[40:43], s34 offen
	s_waitcnt lgkmcnt(4)
	v_mfma_f32_32x32x16_bf16 v[50:65], v[182:185], v[198:201], v[50:65]
	s_waitcnt lgkmcnt(3)
	v_mfma_f32_32x32x16_bf16 v[34:49], v[182:185], v[206:209], v[34:49]
	s_waitcnt vmcnt(31)
	ds_write_b128 v139, v[126:129] offset:50688
	buffer_load_dwordx4 v[126:129], v140, s[24:27], s3 offen
	buffer_load_dwordx4 v[252:255], v140, s[24:27], s3 offen
	v_mfma_f32_32x32x16_bf16 v[18:33], v[190:193], v[198:201], v[18:33]
	v_mfma_f32_32x32x16_bf16 v[2:17], v[190:193], v[206:209], v[2:17]
	s_add_i32 vcc_hi, vcc_hi, 2
	s_add_u32 s0, s0, 0x100
	s_addc_u32 s1, s1, 0
	s_cmp_lt_u32 vcc_hi, 14
	s_waitcnt lgkmcnt(0)
	s_barrier
	s_cbranch_scc1 .LBB0_133
	s_waitcnt vmcnt(6)
	ds_read_b128 v[98:101], v130
	ds_read_b128 v[102:105], v131 offset:36864
	s_waitcnt vmcnt(5)
	ds_read_b128 v[106:109], v130 offset:32
	s_waitcnt vmcnt(4)
	ds_read_b128 v[110:113], v131 offset:36896
	s_waitcnt vmcnt(3)
	ds_read_b128 v[114:117], v131 offset:41472
	s_waitcnt vmcnt(2)
	ds_read_b128 v[118:121], v130 offset:4608
	s_waitcnt vmcnt(1)
	ds_read_b128 v[122:125], v130 offset:4640
	s_waitcnt vmcnt(0)
	ds_read_b128 v[126:129], v131 offset:41504
	s_waitcnt lgkmcnt(3)
	v_mfma_f32_32x32x16_bf16 v[34:49], v[98:101], v[114:117], v[34:49]
	ds_write_b128 v139, v[94:97] offset:18432
	v_mfma_f32_32x32x16_bf16 v[50:65], v[98:101], v[102:105], v[50:65]
	s_waitcnt lgkmcnt(3)
	v_mfma_f32_32x32x16_bf16 v[18:33], v[118:121], v[102:105], v[18:33]
	ds_write_b128 v139, v[90:93] offset:55296
	v_mfma_f32_32x32x16_bf16 v[2:17], v[118:121], v[114:117], v[2:17]
	v_mfma_f32_32x32x16_bf16 v[50:65], v[106:109], v[110:113], v[50:65]
	ds_read_b128 v[90:93], v130 offset:64
	ds_read_b128 v[94:97], v130 offset:4672
	ds_read_b128 v[98:101], v131 offset:36928
	ds_read_b128 v[102:105], v131 offset:41536
	ds_write_b128 v139, v[86:89] offset:23040
	s_waitcnt lgkmcnt(7)
	v_mfma_f32_32x32x16_bf16 v[34:49], v[106:109], v[126:129], v[34:49]
	v_mfma_f32_32x32x16_bf16 v[18:33], v[122:125], v[110:113], v[18:33]
	ds_write_b128 v139, v[82:85] offset:59904
	v_mfma_f32_32x32x16_bf16 v[2:17], v[122:125], v[126:129], v[2:17]
	s_waitcnt lgkmcnt(3)
	v_mfma_f32_32x32x16_bf16 v[50:65], v[90:93], v[98:101], v[50:65]
	ds_read_b128 v[82:85], v130 offset:96
	ds_read_b128 v[86:89], v130 offset:4704
	ds_read_b128 v[106:109], v131 offset:36960
	ds_read_b128 v[110:113], v131 offset:41568
	ds_write_b128 v139, v[78:81] offset:27648
	s_waitcnt lgkmcnt(7)
	v_mfma_f32_32x32x16_bf16 v[34:49], v[90:93], v[102:105], v[34:49]
	v_mfma_f32_32x32x16_bf16 v[18:33], v[94:97], v[98:101], v[18:33]
	ds_write_b128 v139, v[74:77] offset:64512
	v_mfma_f32_32x32x16_bf16 v[2:17], v[94:97], v[102:105], v[2:17]
	s_waitcnt lgkmcnt(3)
	v_mfma_f32_32x32x16_bf16 v[50:65], v[82:85], v[106:109], v[50:65]
	ds_write_b128 v139, v[70:73] offset:32256
	s_waitcnt lgkmcnt(3)
	v_mfma_f32_32x32x16_bf16 v[34:49], v[82:85], v[110:113], v[34:49]
	v_mfma_f32_32x32x16_bf16 v[18:33], v[86:89], v[106:109], v[18:33]
	ds_write_b128 v142, v[66:69] offset:13824
	v_mfma_f32_32x32x16_bf16 v[2:17], v[86:89], v[110:113], v[2:17]
	s_waitcnt lgkmcnt(0)
	s_barrier
	ds_read_b128 v[66:69], v130 offset:18432
	ds_read_b128 v[70:73], v131 offset:55296
	ds_read_b128 v[74:77], v130 offset:18464
	ds_read_b128 v[78:81], v131 offset:55328
	ds_read_b128 v[82:85], v131 offset:59904
	ds_read_b128 v[86:89], v130 offset:23040
	ds_read_b128 v[90:93], v130 offset:23072
	ds_read_b128 v[94:97], v131 offset:59936
	s_waitcnt lgkmcnt(6)
	v_mfma_f32_32x32x16_bf16 v[50:65], v[66:69], v[70:73], v[50:65]
	s_waitcnt lgkmcnt(3)
	v_mfma_f32_32x32x16_bf16 v[34:49], v[66:69], v[82:85], v[34:49]
	s_waitcnt lgkmcnt(2)
	v_mfma_f32_32x32x16_bf16 v[18:33], v[86:89], v[70:73], v[18:33]
	v_mfma_f32_32x32x16_bf16 v[2:17], v[86:89], v[82:85], v[2:17]
	v_mfma_f32_32x32x16_bf16 v[50:65], v[74:77], v[78:81], v[50:65]
	ds_read_b128 v[66:69], v130 offset:18496
	ds_read_b128 v[70:73], v130 offset:23104
	ds_read_b128 v[82:85], v131 offset:55360
	ds_read_b128 v[86:89], v131 offset:59968
	s_waitcnt lgkmcnt(4)
	v_mfma_f32_32x32x16_bf16 v[34:49], v[74:77], v[94:97], v[34:49]
	v_mfma_f32_32x32x16_bf16 v[18:33], v[90:93], v[78:81], v[18:33]
	v_mfma_f32_32x32x16_bf16 v[2:17], v[90:93], v[94:97], v[2:17]
	s_waitcnt lgkmcnt(1)
	v_mfma_f32_32x32x16_bf16 v[50:65], v[66:69], v[82:85], v[50:65]
	ds_read_b128 v[74:77], v130 offset:18528
	ds_read_b128 v[78:81], v130 offset:23136
	ds_read_b128 v[90:93], v131 offset:55392
	ds_read_b128 v[94:97], v131 offset:60000
	s_waitcnt lgkmcnt(4)
	v_mfma_f32_32x32x16_bf16 v[34:49], v[66:69], v[86:89], v[34:49]
	v_mfma_f32_32x32x16_bf16 v[18:33], v[70:73], v[82:85], v[18:33]
	v_mfma_f32_32x32x16_bf16 v[2:17], v[70:73], v[86:89], v[2:17]
	s_waitcnt lgkmcnt(1)
	v_mfma_f32_32x32x16_bf16 v[50:65], v[74:77], v[90:93], v[50:65]
	s_waitcnt lgkmcnt(0)
	v_mfma_f32_32x32x16_bf16 v[34:49], v[74:77], v[94:97], v[34:49]
	v_mfma_f32_32x32x16_bf16 v[18:33], v[78:81], v[90:93], v[18:33]
	v_mfma_f32_32x32x16_bf16 v[2:17], v[78:81], v[94:97], v[2:17]
	v_lshrrev_b32_e32 v227, 5, v136
	s_lshl_b32 s0, s51, 9
	v_lshl_add_u32 v223, v227, 12, v222
	v_add_u32_e32 v223, s0, v223
	v_mov_b32_e32 v228, v223
	global_load_dwordx4 v[98:101], v228, s[68:69]
	v_add_u32_e32 v228, 0x8000, v228
	global_load_dwordx4 v[102:105], v228, s[68:69]
	v_add_u32_e32 v228, 0x8000, v228
	global_load_dwordx4 v[106:109], v228, s[68:69]
	v_add_u32_e32 v228, 0x8000, v228
	global_load_dwordx4 v[110:113], v228, s[68:69]
	v_add_u32_e32 v228, 0x8000, v228
	global_load_dwordx4 v[114:117], v228, s[68:69]
	v_add_u32_e32 v228, 0x8000, v228
	global_load_dwordx4 v[118:121], v228, s[68:69]
	v_add_u32_e32 v228, 0x8000, v228
	global_load_dwordx4 v[122:125], v228, s[68:69]
	v_add_u32_e32 v228, 0x8000, v228
	global_load_dwordx4 v[126:129], v228, s[68:69]
	v_add_u32_e32 v228, 0x8000, v228
	global_load_dwordx4 v[178:181], v228, s[68:69]
	v_add_u32_e32 v228, 0x8000, v228
	global_load_dwordx4 v[182:185], v228, s[68:69]
	v_add_u32_e32 v228, 0x8000, v228
	global_load_dwordx4 v[186:189], v228, s[68:69]
	v_add_u32_e32 v228, 0x8000, v228
	global_load_dwordx4 v[190:193], v228, s[68:69]
	v_add_u32_e32 v228, 0x8000, v228
	global_load_dwordx4 v[194:197], v228, s[68:69]
	v_add_u32_e32 v228, 0x8000, v228
	global_load_dwordx4 v[198:201], v228, s[68:69]
	v_add_u32_e32 v228, 0x8000, v228
	global_load_dwordx4 v[202:205], v228, s[68:69]
	v_add_u32_e32 v228, 0x8000, v228
	global_load_dwordx4 v[206:209], v228, s[68:69]
	v_lshl_or_b32 v66, v138, 2, v141
	s_movk_i32 s0, 0x210
	v_and_or_b32 v67, v136, 64, v137
	v_mul_lo_u32 v66, v66, s0
	v_lshl_add_u32 v66, v67, 2, v66
	s_barrier
	s_nop 3
	ds_write2_b32 v66, v50, v34 offset1:32
	ds_write2_b32 v66, v51, v35 offset0:132 offset1:164
	v_add_u32_e32 v34, 0x400, v66
	ds_write2_b32 v34, v52, v36 offset0:8 offset1:40
	ds_write2_b32 v34, v53, v37 offset0:140 offset1:172
	v_add_u32_e32 v34, 0x1000, v66
	ds_write2_b32 v34, v54, v38 offset0:32 offset1:64
	ds_write2_b32 v34, v55, v39 offset0:164 offset1:196
	v_add_u32_e32 v34, 0x1400, v66
	ds_write2_b32 v34, v56, v40 offset0:40 offset1:72
	ds_write2_b32 v34, v57, v41 offset0:172 offset1:204
	v_add_u32_e32 v34, 0x2000, v66
	ds_write2_b32 v34, v58, v42 offset0:64 offset1:96
	ds_write2_b32 v34, v59, v43 offset0:196 offset1:228
	v_add_u32_e32 v34, 0x2400, v66
	ds_write2_b32 v34, v60, v44 offset0:72 offset1:104
	ds_write2_b32 v34, v61, v45 offset0:204 offset1:236
	v_add_u32_e32 v34, 0x3000, v66
	ds_write2_b32 v34, v62, v46 offset0:96 offset1:128
	v_add_u32_e32 v34, 0x3200, v66
	ds_write2_b32 v34, v63, v47 offset0:100 offset1:132
	v_add_u32_e32 v34, 0x3400, v66
	ds_write2_b32 v34, v64, v48 offset0:104 offset1:136
	v_add_u32_e32 v34, 0x3600, v66
	ds_write2_b32 v34, v65, v49 offset0:108 offset1:140
	v_add_u32_e32 v34, 0x4000, v66
	ds_write2_b32 v34, v18, v2 offset0:128 offset1:160
	v_add_u32_e32 v2, 0x4400, v66
	ds_write2_b32 v2, v19, v3 offset0:4 offset1:36
	ds_write2_b32 v2, v20, v4 offset0:136 offset1:168
	v_add_u32_e32 v2, 0x4800, v66
	ds_write2_b32 v2, v21, v5 offset0:12 offset1:44
	v_add_u32_e32 v2, 0x5000, v66
	ds_write2_b32 v2, v22, v6 offset0:160 offset1:192
	v_add_u32_e32 v2, 0x5400, v66
	ds_write2_b32 v2, v23, v7 offset0:36 offset1:68
	ds_write2_b32 v2, v24, v8 offset0:168 offset1:200
	v_add_u32_e32 v2, 0x5800, v66
	ds_write2_b32 v2, v25, v9 offset0:44 offset1:76
	v_add_u32_e32 v2, 0x6000, v66
	ds_write2_b32 v2, v26, v10 offset0:192 offset1:224
	v_add_u32_e32 v2, 0x6400, v66
	ds_write2_b32 v2, v27, v11 offset0:68 offset1:100
	ds_write2_b32 v2, v28, v12 offset0:200 offset1:232
	v_add_u32_e32 v2, 0x6800, v66
	ds_write2_b32 v2, v29, v13 offset0:76 offset1:108
	v_add_u32_e32 v2, 0x7200, v66
	ds_write2_b32 v2, v30, v14 offset0:96 offset1:128
	v_add_u32_e32 v2, 0x7400, v66
	ds_write2_b32 v2, v31, v15 offset0:100 offset1:132
	v_add_u32_e32 v2, 0x7600, v66
	ds_write2_b32 v2, v32, v16 offset0:104 offset1:136
	v_add_u32_e32 v2, 0x7800, v66
	ds_write2_b32 v2, v33, v17 offset0:108 offset1:140
	s_waitcnt lgkmcnt(0)
	s_barrier
	v_lshrrev_b32_e32 v227, 5, v136
	v_mul_u32_u24_e32 v225, 0x210, v227
	v_add_u32_e32 v225, v225, v222
	ds_read_b128 v[2:5], v225
	ds_read_b128 v[6:9], v225 offset:4224
	ds_read_b128 v[10:13], v225 offset:8448
	ds_read_b128 v[14:17], v225 offset:12672
	ds_read_b128 v[18:21], v225 offset:16896
	ds_read_b128 v[22:25], v225 offset:21120
	ds_read_b128 v[26:29], v225 offset:25344
	ds_read_b128 v[30:33], v225 offset:29568
	ds_read_b128 v[34:37], v225 offset:33792
	ds_read_b128 v[38:41], v225 offset:38016
	ds_read_b128 v[42:45], v225 offset:42240
	ds_read_b128 v[46:49], v225 offset:46464
	ds_read_b128 v[50:53], v225 offset:50688
	ds_read_b128 v[54:57], v225 offset:54912
	ds_read_b128 v[58:61], v225 offset:59136
	ds_read_b128 v[62:65], v225 offset:63360
	v_mul_u32_u24_e32 v224, 0x880, v227
	s_lshl_b32 s0, s51, 8
	v_lshrrev_b32_e32 v228, 1, v222
	v_add3_u32 v224, v224, v228, s0
	v_lshlrev_b32_e32 v226, 2, v227
	s_waitcnt lgkmcnt(0)
	s_waitcnt vmcnt(15)
	v_pk_fma_f32 v[2:3], v[2:3], v[210:211], v[98:99]
	v_pk_fma_f32 v[4:5], v[4:5], v[212:213], v[100:101]
	s_waitcnt vmcnt(14)
	v_pk_fma_f32 v[6:7], v[6:7], v[210:211], v[102:103]
	v_pk_fma_f32 v[8:9], v[8:9], v[212:213], v[104:105]
	s_waitcnt vmcnt(13)
	v_pk_fma_f32 v[10:11], v[10:11], v[210:211], v[106:107]
	v_pk_fma_f32 v[12:13], v[12:13], v[212:213], v[108:109]
	s_waitcnt vmcnt(12)
	v_pk_fma_f32 v[14:15], v[14:15], v[210:211], v[110:111]
	v_pk_fma_f32 v[16:17], v[16:17], v[212:213], v[112:113]
	s_waitcnt vmcnt(11)
	v_pk_fma_f32 v[18:19], v[18:19], v[210:211], v[114:115]
	v_pk_fma_f32 v[20:21], v[20:21], v[212:213], v[116:117]
	s_waitcnt vmcnt(10)
	v_pk_fma_f32 v[22:23], v[22:23], v[210:211], v[118:119]
	v_pk_fma_f32 v[24:25], v[24:25], v[212:213], v[120:121]
	s_waitcnt vmcnt(9)
	v_pk_fma_f32 v[26:27], v[26:27], v[210:211], v[122:123]
	v_pk_fma_f32 v[28:29], v[28:29], v[212:213], v[124:125]
	s_waitcnt vmcnt(8)
	v_pk_fma_f32 v[30:31], v[30:31], v[210:211], v[126:127]
	v_pk_fma_f32 v[32:33], v[32:33], v[212:213], v[128:129]
	s_waitcnt vmcnt(7)
	v_pk_fma_f32 v[34:35], v[34:35], v[210:211], v[178:179]
	v_pk_fma_f32 v[36:37], v[36:37], v[212:213], v[180:181]
	s_waitcnt vmcnt(6)
	v_pk_fma_f32 v[38:39], v[38:39], v[210:211], v[182:183]
	v_pk_fma_f32 v[40:41], v[40:41], v[212:213], v[184:185]
	s_waitcnt vmcnt(5)
	v_pk_fma_f32 v[42:43], v[42:43], v[210:211], v[186:187]
	v_pk_fma_f32 v[44:45], v[44:45], v[212:213], v[188:189]
	s_waitcnt vmcnt(4)
	v_pk_fma_f32 v[46:47], v[46:47], v[210:211], v[190:191]
	v_pk_fma_f32 v[48:49], v[48:49], v[212:213], v[192:193]
	s_waitcnt vmcnt(3)
	v_pk_fma_f32 v[50:51], v[50:51], v[210:211], v[194:195]
	v_pk_fma_f32 v[52:53], v[52:53], v[212:213], v[196:197]
	s_waitcnt vmcnt(2)
	v_pk_fma_f32 v[54:55], v[54:55], v[210:211], v[198:199]
	v_pk_fma_f32 v[56:57], v[56:57], v[212:213], v[200:201]
	s_waitcnt vmcnt(1)
	v_pk_fma_f32 v[58:59], v[58:59], v[210:211], v[202:203]
	v_pk_fma_f32 v[60:61], v[60:61], v[212:213], v[204:205]
	s_waitcnt vmcnt(0)
	v_pk_fma_f32 v[62:63], v[62:63], v[210:211], v[206:207]
	v_pk_fma_f32 v[64:65], v[64:65], v[212:213], v[208:209]
	v_mov_b32_e32 v228, v223
	global_store_dwordx4 v228, v[2:5], s[70:71]
	v_add_u32_e32 v228, 0x8000, v228
	global_store_dwordx4 v228, v[6:9], s[70:71]
	v_add_u32_e32 v228, 0x8000, v228
	global_store_dwordx4 v228, v[10:13], s[70:71]
	v_add_u32_e32 v228, 0x8000, v228
	global_store_dwordx4 v228, v[14:17], s[70:71]
	v_add_u32_e32 v228, 0x8000, v228
	global_store_dwordx4 v228, v[18:21], s[70:71]
	v_add_u32_e32 v228, 0x8000, v228
	global_store_dwordx4 v228, v[22:25], s[70:71]
	v_add_u32_e32 v228, 0x8000, v228
	global_store_dwordx4 v228, v[26:29], s[70:71]
	v_add_u32_e32 v228, 0x8000, v228
	global_store_dwordx4 v228, v[30:33], s[70:71]
	v_add_u32_e32 v228, 0x8000, v228
	global_store_dwordx4 v228, v[34:37], s[70:71]
	v_add_u32_e32 v228, 0x8000, v228
	global_store_dwordx4 v228, v[38:41], s[70:71]
	v_add_u32_e32 v228, 0x8000, v228
	global_store_dwordx4 v228, v[42:45], s[70:71]
	v_add_u32_e32 v228, 0x8000, v228
	global_store_dwordx4 v228, v[46:49], s[70:71]
	v_add_u32_e32 v228, 0x8000, v228
	global_store_dwordx4 v228, v[50:53], s[70:71]
	v_add_u32_e32 v228, 0x8000, v228
	global_store_dwordx4 v228, v[54:57], s[70:71]
	v_add_u32_e32 v228, 0x8000, v228
	global_store_dwordx4 v228, v[58:61], s[70:71]
	v_add_u32_e32 v228, 0x8000, v228
	global_store_dwordx4 v228, v[62:65], s[70:71]
	s_cmp_lg_u64 s[54:55], 0
	s_cbranch_scc0 .LBB0_122
	v_pk_add_f32 v[218:219], v[218:219], 1.0 op_sel_hi:[1,0]
	v_pk_add_f32 v[220:221], v[220:221], 1.0 op_sel_hi:[1,0]
	v_pk_mul_f32 v[214:215], v[214:215], v[218:219]
	v_pk_mul_f32 v[216:217], v[216:217], v[220:221]
	v_pk_mul_f32 v[98:99], v[2:3], v[2:3]
	v_pk_mul_f32 v[100:101], v[4:5], v[4:5]
	v_pk_mul_f32 v[102:103], v[6:7], v[6:7]
	v_pk_mul_f32 v[104:105], v[8:9], v[8:9]
	v_pk_mul_f32 v[106:107], v[10:11], v[10:11]
	v_pk_mul_f32 v[108:109], v[12:13], v[12:13]
	v_pk_mul_f32 v[110:111], v[14:15], v[14:15]
	v_pk_mul_f32 v[112:113], v[16:17], v[16:17]
	v_pk_mul_f32 v[114:115], v[18:19], v[18:19]
	v_pk_mul_f32 v[116:117], v[20:21], v[20:21]
	v_pk_mul_f32 v[118:119], v[22:23], v[22:23]
	v_pk_mul_f32 v[120:121], v[24:25], v[24:25]
	v_pk_mul_f32 v[122:123], v[26:27], v[26:27]
	v_pk_mul_f32 v[124:125], v[28:29], v[28:29]
	v_pk_mul_f32 v[126:127], v[30:31], v[30:31]
	v_pk_mul_f32 v[128:129], v[32:33], v[32:33]
	v_pk_mul_f32 v[178:179], v[34:35], v[34:35]
	v_pk_mul_f32 v[180:181], v[36:37], v[36:37]
	v_pk_mul_f32 v[182:183], v[38:39], v[38:39]
	v_pk_mul_f32 v[184:185], v[40:41], v[40:41]
	v_pk_mul_f32 v[186:187], v[42:43], v[42:43]
	v_pk_mul_f32 v[188:189], v[44:45], v[44:45]
	v_pk_mul_f32 v[190:191], v[46:47], v[46:47]
	v_pk_mul_f32 v[192:193], v[48:49], v[48:49]
	v_pk_mul_f32 v[194:195], v[50:51], v[50:51]
	v_pk_mul_f32 v[196:197], v[52:53], v[52:53]
	v_pk_mul_f32 v[198:199], v[54:55], v[54:55]
	v_pk_mul_f32 v[200:201], v[56:57], v[56:57]
	v_pk_mul_f32 v[202:203], v[58:59], v[58:59]
	v_pk_mul_f32 v[204:205], v[60:61], v[60:61]
	v_pk_mul_f32 v[206:207], v[62:63], v[62:63]
	v_pk_mul_f32 v[208:209], v[64:65], v[64:65]
	v_add_f32_e32 v229, v98, v99
	v_add_f32_e32 v230, v102, v103
	v_add_f32_e32 v231, v106, v107
	v_add_f32_e32 v232, v110, v111
	v_add_f32_e32 v233, v114, v115
	v_add_f32_e32 v234, v118, v119
	v_add_f32_e32 v235, v122, v123
	v_add_f32_e32 v236, v126, v127
	v_add_f32_e32 v237, v178, v179
	v_add_f32_e32 v238, v182, v183
	v_add_f32_e32 v239, v186, v187
	v_add_f32_e32 v240, v190, v191
	v_add_f32_e32 v241, v194, v195
	v_add_f32_e32 v242, v198, v199
	v_add_f32_e32 v243, v202, v203
	v_add_f32_e32 v244, v206, v207
	v_add_f32_e32 v229, v229, v100
	v_add_f32_e32 v230, v230, v104
	v_add_f32_e32 v231, v231, v108
	v_add_f32_e32 v232, v232, v112
	v_add_f32_e32 v233, v233, v116
	v_add_f32_e32 v234, v234, v120
	v_add_f32_e32 v235, v235, v124
	v_add_f32_e32 v236, v236, v128
	v_add_f32_e32 v237, v237, v180
	v_add_f32_e32 v238, v238, v184
	v_add_f32_e32 v239, v239, v188
	v_add_f32_e32 v240, v240, v192
	v_add_f32_e32 v241, v241, v196
	v_add_f32_e32 v242, v242, v200
	v_add_f32_e32 v243, v243, v204
	v_add_f32_e32 v244, v244, v208
	v_add_f32_e32 v229, v229, v101
	v_add_f32_e32 v230, v230, v105
	v_add_f32_e32 v231, v231, v109
	v_add_f32_e32 v232, v232, v113
	v_add_f32_e32 v233, v233, v117
	v_add_f32_e32 v234, v234, v121
	v_add_f32_e32 v235, v235, v125
	v_add_f32_e32 v236, v236, v129
	v_add_f32_e32 v237, v237, v181
	v_add_f32_e32 v238, v238, v185
	v_add_f32_e32 v239, v239, v189
	v_add_f32_e32 v240, v240, v193
	v_add_f32_e32 v241, v241, v197
	v_add_f32_e32 v242, v242, v201
	v_add_f32_e32 v243, v243, v205
	v_add_f32_e32 v244, v244, v209
	v_pk_mul_f32 v[2:3], v[2:3], v[214:215]
	v_pk_mul_f32 v[4:5], v[4:5], v[216:217]
	v_pk_mul_f32 v[6:7], v[6:7], v[214:215]
	v_pk_mul_f32 v[8:9], v[8:9], v[216:217]
	v_pk_mul_f32 v[10:11], v[10:11], v[214:215]
	v_pk_mul_f32 v[12:13], v[12:13], v[216:217]
	v_pk_mul_f32 v[14:15], v[14:15], v[214:215]
	v_pk_mul_f32 v[16:17], v[16:17], v[216:217]
	v_pk_mul_f32 v[18:19], v[18:19], v[214:215]
	v_pk_mul_f32 v[20:21], v[20:21], v[216:217]
	v_pk_mul_f32 v[22:23], v[22:23], v[214:215]
	v_pk_mul_f32 v[24:25], v[24:25], v[216:217]
	v_pk_mul_f32 v[26:27], v[26:27], v[214:215]
	v_pk_mul_f32 v[28:29], v[28:29], v[216:217]
	v_pk_mul_f32 v[30:31], v[30:31], v[214:215]
	v_pk_mul_f32 v[32:33], v[32:33], v[216:217]
	v_pk_mul_f32 v[34:35], v[34:35], v[214:215]
	v_pk_mul_f32 v[36:37], v[36:37], v[216:217]
	v_pk_mul_f32 v[38:39], v[38:39], v[214:215]
	v_pk_mul_f32 v[40:41], v[40:41], v[216:217]
	v_pk_mul_f32 v[42:43], v[42:43], v[214:215]
	v_pk_mul_f32 v[44:45], v[44:45], v[216:217]
	v_pk_mul_f32 v[46:47], v[46:47], v[214:215]
	v_pk_mul_f32 v[48:49], v[48:49], v[216:217]
	v_pk_mul_f32 v[50:51], v[50:51], v[214:215]
	v_pk_mul_f32 v[52:53], v[52:53], v[216:217]
	v_pk_mul_f32 v[54:55], v[54:55], v[214:215]
	v_pk_mul_f32 v[56:57], v[56:57], v[216:217]
	v_pk_mul_f32 v[58:59], v[58:59], v[214:215]
	v_pk_mul_f32 v[60:61], v[60:61], v[216:217]
	v_pk_mul_f32 v[62:63], v[62:63], v[214:215]
	v_pk_mul_f32 v[64:65], v[64:65], v[216:217]
	v_cvt_pk_bf16_f32 v98, v2, v3
	v_cvt_pk_bf16_f32 v99, v4, v5
	v_cvt_pk_bf16_f32 v102, v6, v7
	v_cvt_pk_bf16_f32 v103, v8, v9
	v_cvt_pk_bf16_f32 v106, v10, v11
	v_cvt_pk_bf16_f32 v107, v12, v13
	v_cvt_pk_bf16_f32 v110, v14, v15
	v_cvt_pk_bf16_f32 v111, v16, v17
	v_cvt_pk_bf16_f32 v114, v18, v19
	v_cvt_pk_bf16_f32 v115, v20, v21
	v_cvt_pk_bf16_f32 v118, v22, v23
	v_cvt_pk_bf16_f32 v119, v24, v25
	v_cvt_pk_bf16_f32 v122, v26, v27
	v_cvt_pk_bf16_f32 v123, v28, v29
	v_cvt_pk_bf16_f32 v126, v30, v31
	v_cvt_pk_bf16_f32 v127, v32, v33
	v_cvt_pk_bf16_f32 v178, v34, v35
	v_cvt_pk_bf16_f32 v179, v36, v37
	v_cvt_pk_bf16_f32 v182, v38, v39
	v_cvt_pk_bf16_f32 v183, v40, v41
	v_cvt_pk_bf16_f32 v186, v42, v43
	v_cvt_pk_bf16_f32 v187, v44, v45
	v_cvt_pk_bf16_f32 v190, v46, v47
	v_cvt_pk_bf16_f32 v191, v48, v49
	v_cvt_pk_bf16_f32 v194, v50, v51
	v_cvt_pk_bf16_f32 v195, v52, v53
	v_cvt_pk_bf16_f32 v198, v54, v55
	v_cvt_pk_bf16_f32 v199, v56, v57
	v_cvt_pk_bf16_f32 v202, v58, v59
	v_cvt_pk_bf16_f32 v203, v60, v61
	v_cvt_pk_bf16_f32 v206, v62, v63
	v_cvt_pk_bf16_f32 v207, v64, v65
	v_readlane_b32 s56, v248, 13
	v_readlane_b32 s57, v248, 14
	s_mul_i32 s0, s51, 0xa000
	s_lshl_b32 s1, s2, 2
	s_add_i32 s0, s0, s1
	s_add_u32 s56, s56, s0
	s_addc_u32 s57, s57, 0
	s_mul_i32 s0, s2, 0x880
	s_add_u32 s58, s8, s0
	s_addc_u32 s59, s9, 0
	v_mov_b32_e32 v228, v224
	global_store_dwordx2 v228, v[98:99], s[58:59]
	v_add_u32_e32 v228, 0x4400, v228
	global_store_dwordx2 v228, v[102:103], s[58:59]
	v_add_u32_e32 v228, 0x4400, v228
	global_store_dwordx2 v228, v[106:107], s[58:59]
	v_add_u32_e32 v228, 0x4400, v228
	global_store_dwordx2 v228, v[110:111], s[58:59]
	v_add_u32_e32 v228, 0x4400, v228
	global_store_dwordx2 v228, v[114:115], s[58:59]
	v_add_u32_e32 v228, 0x4400, v228
	global_store_dwordx2 v228, v[118:119], s[58:59]
	v_add_u32_e32 v228, 0x4400, v228
	global_store_dwordx2 v228, v[122:123], s[58:59]
	v_add_u32_e32 v228, 0x4400, v228
	global_store_dwordx2 v228, v[126:127], s[58:59]
	v_add_u32_e32 v228, 0x4400, v228
	global_store_dwordx2 v228, v[178:179], s[58:59]
	v_add_u32_e32 v228, 0x4400, v228
	global_store_dwordx2 v228, v[182:183], s[58:59]
	v_add_u32_e32 v228, 0x4400, v228
	global_store_dwordx2 v228, v[186:187], s[58:59]
	v_add_u32_e32 v228, 0x4400, v228
	global_store_dwordx2 v228, v[190:191], s[58:59]
	v_add_u32_e32 v228, 0x4400, v228
	global_store_dwordx2 v228, v[194:195], s[58:59]
	v_add_u32_e32 v228, 0x4400, v228
	global_store_dwordx2 v228, v[198:199], s[58:59]
	v_add_u32_e32 v228, 0x4400, v228
	global_store_dwordx2 v228, v[202:203], s[58:59]
	v_add_u32_e32 v228, 0x4400, v228
	global_store_dwordx2 v228, v[206:207], s[58:59]
	v_add_f32_dpp v229, v229, v229 quad_perm:[1,0,3,2] row_mask:0xf bank_mask:0xf
	v_add_f32_dpp v230, v230, v230 quad_perm:[1,0,3,2] row_mask:0xf bank_mask:0xf
	v_add_f32_dpp v231, v231, v231 quad_perm:[1,0,3,2] row_mask:0xf bank_mask:0xf
	v_add_f32_dpp v232, v232, v232 quad_perm:[1,0,3,2] row_mask:0xf bank_mask:0xf
	v_add_f32_dpp v233, v233, v233 quad_perm:[1,0,3,2] row_mask:0xf bank_mask:0xf
	v_add_f32_dpp v234, v234, v234 quad_perm:[1,0,3,2] row_mask:0xf bank_mask:0xf
	v_add_f32_dpp v235, v235, v235 quad_perm:[1,0,3,2] row_mask:0xf bank_mask:0xf
	v_add_f32_dpp v236, v236, v236 quad_perm:[1,0,3,2] row_mask:0xf bank_mask:0xf
	v_add_f32_dpp v237, v237, v237 quad_perm:[1,0,3,2] row_mask:0xf bank_mask:0xf
	v_add_f32_dpp v238, v238, v238 quad_perm:[1,0,3,2] row_mask:0xf bank_mask:0xf
	v_add_f32_dpp v239, v239, v239 quad_perm:[1,0,3,2] row_mask:0xf bank_mask:0xf
	v_add_f32_dpp v240, v240, v240 quad_perm:[1,0,3,2] row_mask:0xf bank_mask:0xf
	v_add_f32_dpp v241, v241, v241 quad_perm:[1,0,3,2] row_mask:0xf bank_mask:0xf
	v_add_f32_dpp v242, v242, v242 quad_perm:[1,0,3,2] row_mask:0xf bank_mask:0xf
	v_add_f32_dpp v243, v243, v243 quad_perm:[1,0,3,2] row_mask:0xf bank_mask:0xf
	v_add_f32_dpp v244, v244, v244 quad_perm:[1,0,3,2] row_mask:0xf bank_mask:0xf
	v_add_f32_dpp v229, v229, v229 quad_perm:[2,3,0,1] row_mask:0xf bank_mask:0xf
	v_add_f32_dpp v230, v230, v230 quad_perm:[2,3,0,1] row_mask:0xf bank_mask:0xf
	v_add_f32_dpp v231, v231, v231 quad_perm:[2,3,0,1] row_mask:0xf bank_mask:0xf
	v_add_f32_dpp v232, v232, v232 quad_perm:[2,3,0,1] row_mask:0xf bank_mask:0xf
	v_add_f32_dpp v233, v233, v233 quad_perm:[2,3,0,1] row_mask:0xf bank_mask:0xf
	v_add_f32_dpp v234, v234, v234 quad_perm:[2,3,0,1] row_mask:0xf bank_mask:0xf
	v_add_f32_dpp v235, v235, v235 quad_perm:[2,3,0,1] row_mask:0xf bank_mask:0xf
	v_add_f32_dpp v236, v236, v236 quad_perm:[2,3,0,1] row_mask:0xf bank_mask:0xf
	v_add_f32_dpp v237, v237, v237 quad_perm:[2,3,0,1] row_mask:0xf bank_mask:0xf
	v_add_f32_dpp v238, v238, v238 quad_perm:[2,3,0,1] row_mask:0xf bank_mask:0xf
	v_add_f32_dpp v239, v239, v239 quad_perm:[2,3,0,1] row_mask:0xf bank_mask:0xf
	v_add_f32_dpp v240, v240, v240 quad_perm:[2,3,0,1] row_mask:0xf bank_mask:0xf
	v_add_f32_dpp v241, v241, v241 quad_perm:[2,3,0,1] row_mask:0xf bank_mask:0xf
	v_add_f32_dpp v242, v242, v242 quad_perm:[2,3,0,1] row_mask:0xf bank_mask:0xf
	v_add_f32_dpp v243, v243, v243 quad_perm:[2,3,0,1] row_mask:0xf bank_mask:0xf
	v_add_f32_dpp v244, v244, v244 quad_perm:[2,3,0,1] row_mask:0xf bank_mask:0xf
	v_add_f32_dpp v229, v229, v229 row_ror:4 row_mask:0xf bank_mask:0xf
	v_add_f32_dpp v230, v230, v230 row_ror:4 row_mask:0xf bank_mask:0xf
	v_add_f32_dpp v231, v231, v231 row_ror:4 row_mask:0xf bank_mask:0xf
	v_add_f32_dpp v232, v232, v232 row_ror:4 row_mask:0xf bank_mask:0xf
	v_add_f32_dpp v233, v233, v233 row_ror:4 row_mask:0xf bank_mask:0xf
	v_add_f32_dpp v234, v234, v234 row_ror:4 row_mask:0xf bank_mask:0xf
	v_add_f32_dpp v235, v235, v235 row_ror:4 row_mask:0xf bank_mask:0xf
	v_add_f32_dpp v236, v236, v236 row_ror:4 row_mask:0xf bank_mask:0xf
	v_add_f32_dpp v237, v237, v237 row_ror:4 row_mask:0xf bank_mask:0xf
	v_add_f32_dpp v238, v238, v238 row_ror:4 row_mask:0xf bank_mask:0xf
	v_add_f32_dpp v239, v239, v239 row_ror:4 row_mask:0xf bank_mask:0xf
	v_add_f32_dpp v240, v240, v240 row_ror:4 row_mask:0xf bank_mask:0xf
	v_add_f32_dpp v241, v241, v241 row_ror:4 row_mask:0xf bank_mask:0xf
	v_add_f32_dpp v242, v242, v242 row_ror:4 row_mask:0xf bank_mask:0xf
	v_add_f32_dpp v243, v243, v243 row_ror:4 row_mask:0xf bank_mask:0xf
	v_add_f32_dpp v244, v244, v244 row_ror:4 row_mask:0xf bank_mask:0xf
	v_add_f32_dpp v229, v229, v229 row_ror:8 row_mask:0xf bank_mask:0xf
	v_add_f32_dpp v230, v230, v230 row_ror:8 row_mask:0xf bank_mask:0xf
	v_add_f32_dpp v231, v231, v231 row_ror:8 row_mask:0xf bank_mask:0xf
	v_add_f32_dpp v232, v232, v232 row_ror:8 row_mask:0xf bank_mask:0xf
	v_add_f32_dpp v233, v233, v233 row_ror:8 row_mask:0xf bank_mask:0xf
	v_add_f32_dpp v234, v234, v234 row_ror:8 row_mask:0xf bank_mask:0xf
	v_add_f32_dpp v235, v235, v235 row_ror:8 row_mask:0xf bank_mask:0xf
	v_add_f32_dpp v236, v236, v236 row_ror:8 row_mask:0xf bank_mask:0xf
	v_add_f32_dpp v237, v237, v237 row_ror:8 row_mask:0xf bank_mask:0xf
	v_add_f32_dpp v238, v238, v238 row_ror:8 row_mask:0xf bank_mask:0xf
	v_add_f32_dpp v239, v239, v239 row_ror:8 row_mask:0xf bank_mask:0xf
	v_add_f32_dpp v240, v240, v240 row_ror:8 row_mask:0xf bank_mask:0xf
	v_add_f32_dpp v241, v241, v241 row_ror:8 row_mask:0xf bank_mask:0xf
	v_add_f32_dpp v242, v242, v242 row_ror:8 row_mask:0xf bank_mask:0xf
	v_add_f32_dpp v243, v243, v243 row_ror:8 row_mask:0xf bank_mask:0xf
	v_add_f32_dpp v244, v244, v244 row_ror:8 row_mask:0xf bank_mask:0xf
	v_add_f32_dpp v229, v229, v229 row_bcast:15 row_mask:0xa bank_mask:0xf
	v_add_f32_dpp v230, v230, v230 row_bcast:15 row_mask:0xa bank_mask:0xf
	v_add_f32_dpp v231, v231, v231 row_bcast:15 row_mask:0xa bank_mask:0xf
	v_add_f32_dpp v232, v232, v232 row_bcast:15 row_mask:0xa bank_mask:0xf
	v_add_f32_dpp v233, v233, v233 row_bcast:15 row_mask:0xa bank_mask:0xf
	v_add_f32_dpp v234, v234, v234 row_bcast:15 row_mask:0xa bank_mask:0xf
	v_add_f32_dpp v235, v235, v235 row_bcast:15 row_mask:0xa bank_mask:0xf
	v_add_f32_dpp v236, v236, v236 row_bcast:15 row_mask:0xa bank_mask:0xf
	v_add_f32_dpp v237, v237, v237 row_bcast:15 row_mask:0xa bank_mask:0xf
	v_add_f32_dpp v238, v238, v238 row_bcast:15 row_mask:0xa bank_mask:0xf
	v_add_f32_dpp v239, v239, v239 row_bcast:15 row_mask:0xa bank_mask:0xf
	v_add_f32_dpp v240, v240, v240 row_bcast:15 row_mask:0xa bank_mask:0xf
	v_add_f32_dpp v241, v241, v241 row_bcast:15 row_mask:0xa bank_mask:0xf
	v_add_f32_dpp v242, v242, v242 row_bcast:15 row_mask:0xa bank_mask:0xf
	v_add_f32_dpp v243, v243, v243 row_bcast:15 row_mask:0xa bank_mask:0xf
	v_add_f32_dpp v244, v244, v244 row_bcast:15 row_mask:0xa bank_mask:0xf
	s_mov_b64 s[40:41], exec
	s_mov_b32 s0, 0x80000000
	s_mov_b32 s1, 0x80000000
	s_mov_b64 exec, s[0:1]
	global_store_dword v226, v229, s[56:57]
	global_store_dword v226, v230, s[56:57] offset:32
	global_store_dword v226, v231, s[56:57] offset:64
	global_store_dword v226, v232, s[56:57] offset:96
	global_store_dword v226, v233, s[56:57] offset:128
	global_store_dword v226, v234, s[56:57] offset:160
	global_store_dword v226, v235, s[56:57] offset:192
	global_store_dword v226, v236, s[56:57] offset:224
	global_store_dword v226, v237, s[56:57] offset:256
	global_store_dword v226, v238, s[56:57] offset:288
	global_store_dword v226, v239, s[56:57] offset:320
	global_store_dword v226, v240, s[56:57] offset:352
	global_store_dword v226, v241, s[56:57] offset:384
	global_store_dword v226, v242, s[56:57] offset:416
	global_store_dword v226, v243, s[56:57] offset:448
	global_store_dword v226, v244, s[56:57] offset:480
	s_mov_b64 exec, s[40:41]
	s_branch .LBB0_122

	.amdhsa_kernel _Z11mega_kernel6Paramsii
		.amdhsa_group_segment_fixed_size 73760
		.amdhsa_private_segment_fixed_size 0
		.amdhsa_kernarg_size 600
		.amdhsa_user_sgpr_count 2
		.amdhsa_user_sgpr_dispatch_ptr 0
		.amdhsa_user_sgpr_queue_ptr 0
		.amdhsa_user_sgpr_kernarg_segment_ptr 1
		.amdhsa_user_sgpr_dispatch_id 0
		.amdhsa_user_sgpr_kernarg_preload_length 0
		.amdhsa_user_sgpr_kernarg_preload_offset 0
		.amdhsa_user_sgpr_private_segment_size 0
		.amdhsa_uses_dynamic_stack 0
		.amdhsa_enable_private_segment 0
		.amdhsa_system_sgpr_workgroup_id_x 1
		.amdhsa_system_sgpr_workgroup_id_y 0
		.amdhsa_system_sgpr_workgroup_id_z 0
		.amdhsa_system_sgpr_workgroup_info 0
		.amdhsa_system_vgpr_workitem_id 0
		.amdhsa_next_free_vgpr 256
		.amdhsa_next_free_sgpr 100
		.amdhsa_accum_offset 256
		.amdhsa_reserve_vcc 1
		.amdhsa_float_round_mode_32 0
		.amdhsa_float_round_mode_16_64 0
		.amdhsa_float_denorm_mode_32 3
		.amdhsa_float_denorm_mode_16_64 3
		.amdhsa_dx10_clamp 1
		.amdhsa_ieee_mode 1
		.amdhsa_fp16_overflow 0
		.amdhsa_tg_split 0
		.amdhsa_exception_fp_ieee_invalid_op 0
		.amdhsa_exception_fp_denorm_src 0
		.amdhsa_exception_fp_ieee_div_zero 0
		.amdhsa_exception_fp_ieee_overflow 0
		.amdhsa_exception_fp_ieee_underflow 0
		.amdhsa_exception_fp_ieee_inexact 0
		.amdhsa_exception_int_div_zero 0
	.end_amdhsa_kernel

amdhsa.kernels:
  - .agpr_count:     0
    .args:
      - .offset:         0
        .size:           336
        .value_kind:     by_value
      - .offset:         336
        .size:           4
        .value_kind:     by_value
      - .offset:         340
        .size:           4
        .value_kind:     by_value
      - .offset:         344
        .size:           4
        .value_kind:     hidden_block_count_x
      - .offset:         348
        .size:           4
        .value_kind:     hidden_block_count_y
      - .offset:         352
        .size:           4
        .value_kind:     hidden_block_count_z
      - .offset:         356
        .size:           2
        .value_kind:     hidden_group_size_x
      - .offset:         358
        .size:           2
        .value_kind:     hidden_group_size_y
      - .offset:         360
        .size:           2
        .value_kind:     hidden_group_size_z
      - .offset:         362
        .size:           2
        .value_kind:     hidden_remainder_x
      - .offset:         364
        .size:           2
        .value_kind:     hidden_remainder_y
      - .offset:         366
        .size:           2
        .value_kind:     hidden_remainder_z
      - .offset:         384
        .size:           8
        .value_kind:     hidden_global_offset_x
      - .offset:         392
        .size:           8
        .value_kind:     hidden_global_offset_y
      - .offset:         400
        .size:           8
        .value_kind:     hidden_global_offset_z
      - .offset:         408
        .size:           2
        .value_kind:     hidden_grid_dims
    .group_segment_fixed_size: 73760
    .kernarg_segment_align: 8
    .kernarg_segment_size: 600
    .language:       OpenCL C
    .language_version:
      - 2
      - 0
    .max_flat_workgroup_size: 256
    .name:           _Z11mega_kernel6Paramsii
    .private_segment_fixed_size: 0
    .sgpr_count:     106
    .sgpr_spill_count: 179
    .symbol:         _Z11mega_kernel6Paramsii.kd
    .uniform_work_group_size: 1
    .uses_dynamic_stack: false
    .vgpr_count:     256
    .vgpr_spill_count: 0
    .wavefront_size: 64
